# attention KV loop back edge rotated: row-sum restore moved above the exit test so each iteration ends in one taken branch instead of a not-taken branch plus an unconditional jump
# speedup vs baseline: 1.0028x; 1.0028x over previous
; #define SBAR() __builtin_amdgcn_sched_barrier(0)
; #define STEP(D, CUR, NXT) v_load<D + 1>(NXT, vb); asm volatile("s_waitcnt lgkmcnt(8)" ::: "memory"); SBAR(); pv_mma(o[D], CUR, pa0, pa1, pa2, pa3); SBAR();
; __device__ __forceinline__ void partialSM(f32x16& p0, f32x16& p1, float& m_reg, float& mn, float& alpha) {
;     ...
;   float mnC = -mn * C;
; #pragma unroll
;   for (int r = 0; r < 16; ++r) p0[r] = fmaf(p0[r], C, mnC);
; #pragma unroll
;   for (int r = 0; r < 16; ++r) p1[r] = fmaf(p1[r], C, mnC);
; #pragma unroll
;   for (int r = 0; r < 16; ++r) p0[r] = __builtin_amdgcn_exp2f(p0[r]);
; }
; __device__ __forceinline__ void finishSM(f32x16& p0, f32x16& p1, float alpha, float& l_reg, bf16x8& pa0, bf16x8& pa1, bf16x8& pa2, bf16x8& pa3) {
; #pragma unroll
;   for (int r = 0; r < 16; ++r) p1[r] = __builtin_amdgcn_exp2f(p1[r]);
;   float ps = 0;
; #pragma unroll
;   for (int r = 0; r < 16; ++r) ps += p0[r];
; #pragma unroll
;   for (int r = 0; r < 16; ++r) ps += p1[r];
;   { auto rr = __builtin_amdgcn_permlane32_swap(__float_as_uint(ps), __float_as_uint(ps), false, false);
;     ps = __uint_as_float(rr[0]) + __uint_as_float(rr[1]); }
;   l_reg = l_reg * alpha + ps;
;     ...
;   PK4(p0, 0, pa0); PK4(p0, 8, pa1); PK4(p1, 0, pa2); PK4(p1, 8, pa3);
; __device__ __forceinline__ void pv_all(f32x16* o, int vb, bf16x8 pa0, bf16x8 pa1, bf16x8 pa2, bf16x8 pa3) {
;   VFrag fa, fb;
;   v_load<0>(fa, vb);
;     ...
;   STEP(0, fa, fb) STEP(1, fb, fa) STEP(2, fa, fb) STEP(3, fb, fa) STEP(4, fa, fb) STEP(5, fb, fa) STEP(6, fa, fb)
;     ...
;   asm volatile("s_waitcnt lgkmcnt(0)" ::: "memory"); SBAR(); pv_mma(o[7], fb, pa0, pa1, pa2, pa3);
; }
.LBB0_624:
	v_mul_f32_e32 v194, 0xbe0293ee, v243
	v_fmamk_f32 v146, v146, 0x3e0293ee, v194
	v_fmamk_f32 v147, v147, 0x3e0293ee, v194
	v_fmamk_f32 v148, v148, 0x3e0293ee, v194
	v_fmamk_f32 v149, v149, 0x3e0293ee, v194
	v_fmamk_f32 v150, v150, 0x3e0293ee, v194
	v_fmamk_f32 v151, v151, 0x3e0293ee, v194
	v_fmamk_f32 v152, v152, 0x3e0293ee, v194
	v_fmamk_f32 v153, v153, 0x3e0293ee, v194
	v_fmamk_f32 v154, v154, 0x3e0293ee, v194
	v_fmamk_f32 v155, v155, 0x3e0293ee, v194
	v_fmamk_f32 v156, v156, 0x3e0293ee, v194
	v_fmamk_f32 v157, v157, 0x3e0293ee, v194
	v_fmamk_f32 v158, v158, 0x3e0293ee, v194
	v_fmamk_f32 v159, v159, 0x3e0293ee, v194
	v_fmamk_f32 v160, v160, 0x3e0293ee, v194
	v_fmamk_f32 v161, v161, 0x3e0293ee, v194
	v_fmamk_f32 v130, v130, 0x3e0293ee, v194
	v_fmamk_f32 v131, v131, 0x3e0293ee, v194
	v_fmamk_f32 v132, v132, 0x3e0293ee, v194
	v_fmamk_f32 v133, v133, 0x3e0293ee, v194
	v_fmamk_f32 v134, v134, 0x3e0293ee, v194
	v_fmamk_f32 v135, v135, 0x3e0293ee, v194
	v_fmamk_f32 v136, v136, 0x3e0293ee, v194
	v_fmamk_f32 v137, v137, 0x3e0293ee, v194
	v_fmamk_f32 v138, v138, 0x3e0293ee, v194
	v_fmamk_f32 v139, v139, 0x3e0293ee, v194
	v_fmamk_f32 v140, v140, 0x3e0293ee, v194
	v_fmamk_f32 v141, v141, 0x3e0293ee, v194
	v_fmamk_f32 v142, v142, 0x3e0293ee, v194
	v_fmamk_f32 v143, v143, 0x3e0293ee, v194
	v_fmamk_f32 v144, v144, 0x3e0293ee, v194
	v_fmac_f32_e32 v194, 0x3e0293ee, v145
	v_exp_f32_e32 v145, v146
	v_exp_f32_e32 v147, v147
	v_exp_f32_e32 v148, v148
	v_exp_f32_e32 v149, v149
	v_exp_f32_e32 v150, v150
	v_exp_f32_e32 v195, v130
	v_add_f32_e32 v130, 0, v145
	v_exp_f32_e32 v151, v151
	v_add_f32_e32 v130, v147, v130
	v_exp_f32_e32 v152, v152
	v_add_f32_e32 v130, v148, v130
	v_exp_f32_e32 v153, v153
	v_add_f32_e32 v130, v149, v130
	v_exp_f32_e32 v154, v154
	v_add_f32_e32 v130, v150, v130
	v_exp_f32_e32 v155, v155
	v_add_f32_e32 v130, v151, v130
	v_exp_f32_e32 v156, v156
	v_add_f32_e32 v130, v152, v130
	v_exp_f32_e32 v157, v157
	v_add_f32_e32 v130, v153, v130
	v_exp_f32_e32 v158, v158
	v_add_f32_e32 v130, v154, v130
	v_exp_f32_e32 v159, v159
	v_add_f32_e32 v130, v155, v130
	v_exp_f32_e32 v160, v160
	v_add_f32_e32 v130, v156, v130
	v_exp_f32_e32 v161, v161
	v_add_f32_e32 v130, v157, v130
	v_add_f32_e32 v130, v158, v130
	v_exp_f32_e32 v196, v131
	v_add_f32_e32 v130, v159, v130
	v_exp_f32_e32 v197, v132
	v_add_f32_e32 v130, v160, v130
	v_exp_f32_e32 v198, v133
	v_add_f32_e32 v130, v161, v130
	v_exp_f32_e32 v199, v134
	v_add_f32_e32 v130, v195, v130
	v_exp_f32_e32 v200, v135
	v_add_f32_e32 v130, v196, v130
	v_exp_f32_e32 v201, v136
	v_add_f32_e32 v130, v197, v130
	v_exp_f32_e32 v202, v137
	v_add_f32_e32 v130, v198, v130
	v_exp_f32_e32 v203, v138
	v_add_f32_e32 v130, v199, v130
	v_exp_f32_e32 v204, v139
	v_add_f32_e32 v130, v200, v130
	v_exp_f32_e32 v205, v140
	v_add_f32_e32 v130, v201, v130
	v_exp_f32_e32 v206, v141
	v_add_f32_e32 v130, v202, v130
	v_exp_f32_e32 v207, v142
	v_add_f32_e32 v130, v203, v130
	v_exp_f32_e32 v208, v143
	v_add_f32_e32 v130, v204, v130
	v_exp_f32_e32 v209, v144
	v_add_f32_e32 v130, v205, v130
	v_exp_f32_e32 v194, v194
	v_add_f32_e32 v130, v206, v130
	v_add_f32_e32 v130, v207, v130
	v_add_f32_e32 v130, v208, v130
	v_add_f32_e32 v130, v209, v130
	v_add_f32_e32 v130, v194, v130
	v_mov_b32_e32 v131, v130
	s_nop 1
	v_permlane32_swap_b32_e32 v130, v131
	v_add_f32_e32 v146, v130, v131
	v_fmac_f32_e32 v146, v244, v1
	v_cvt_pk_bf16_f32 v130, v145, v147
	v_cvt_pk_bf16_f32 v131, v148, v149
	v_cvt_pk_bf16_f32 v132, v150, v151
	v_cvt_pk_bf16_f32 v133, v152, v153
	v_cvt_pk_bf16_f32 v134, v154, v155
	v_cvt_pk_bf16_f32 v135, v156, v157
	v_cvt_pk_bf16_f32 v136, v158, v159
	v_cvt_pk_bf16_f32 v137, v160, v161
	v_cvt_pk_bf16_f32 v138, v195, v196
	v_cvt_pk_bf16_f32 v139, v197, v198
	v_cvt_pk_bf16_f32 v140, v199, v200
	v_cvt_pk_bf16_f32 v141, v201, v202
	v_cvt_pk_bf16_f32 v142, v203, v204
	v_cvt_pk_bf16_f32 v143, v205, v206
	v_cvt_pk_bf16_f32 v144, v207, v208
	v_cvt_pk_bf16_f32 v145, v209, v194
	s_nop 0
	v_permlane32_swap_b32_e32 v130, v132
	v_permlane32_swap_b32_e32 v131, v133
	v_permlane32_swap_b32_e32 v134, v136
	v_permlane32_swap_b32_e32 v135, v137
	v_permlane32_swap_b32_e32 v138, v140
	v_permlane32_swap_b32_e32 v139, v141
	v_permlane32_swap_b32_e32 v142, v144
	v_permlane32_swap_b32_e32 v143, v145
	ds_read_b64_tr_b16 v[156:157], v251 offset:512
	ds_read_b64_tr_b16 v[158:159], v251 offset:4608
	ds_read_b64_tr_b16 v[194:195], v251 offset:8704
	ds_read_b64_tr_b16 v[196:197], v251 offset:12800
	ds_read_b64_tr_b16 v[198:199], v251 offset:1024
	ds_read_b64_tr_b16 v[200:201], v251 offset:5120
	ds_read_b64_tr_b16 v[202:203], v251 offset:9216
	ds_read_b64_tr_b16 v[204:205], v251 offset:13312
	s_waitcnt lgkmcnt(8)
	v_mfma_f32_32x32x16_bf16 v[114:129], v[130:133], v[246:249], v[114:129]
	ds_read_b64_tr_b16 v[148:149], v251 offset:1536
	ds_read_b64_tr_b16 v[150:151], v251 offset:5632
	ds_read_b64_tr_b16 v[152:153], v251 offset:9728
	ds_read_b64_tr_b16 v[154:155], v251 offset:13824
	v_mfma_f32_32x32x16_bf16 v[114:129], v[134:137], v[252:255], v[114:129]
	s_waitcnt lgkmcnt(8)
; #define SBAR() __builtin_amdgcn_sched_barrier(0)
; __device__ __forceinline__ int crow(int r, int hi) { return (r & 3) + 8 * (r >> 2) + 4 * hi; }
; #define STEP(D, CUR, NXT) v_load<D + 1>(NXT, vb); asm volatile("s_waitcnt lgkmcnt(8)" ::: "memory"); SBAR(); pv_mma(o[D], CUR, pa0, pa1, pa2, pa3); SBAR();
; __device__ __forceinline__ void pv_all(f32x16* o, int vb, bf16x8 pa0, bf16x8 pa1, bf16x8 pa2, bf16x8 pa3) {
;   VFrag fa, fb;
;   v_load<0>(fa, vb);
;     ...
;   STEP(0, fa, fb) STEP(1, fb, fa) STEP(2, fa, fb) STEP(3, fb, fa) STEP(4, fa, fb) STEP(5, fb, fa) STEP(6, fa, fb)
;     ...
;   asm volatile("s_waitcnt lgkmcnt(0)" ::: "memory"); SBAR(); pv_mma(o[7], fb, pa0, pa1, pa2, pa3);
; }
; __device__ __forceinline__ void body(const bf16_t* __restrict__ Qb, const bf16_t* __restrict__ Kh, const bf16_t* __restrict__ Vh, bf16_t* __restrict__ Ob, int seq, char* lds) {
;     ...
;   for (int j = 0; j < NT; ++j) {
;     const int b = j & 1;
;     f32x16 p0, p1; float mn, al; bf16x8 pa0, pa1, pa2, pa3;
;     if (j + 1 < NT) STAGE(b ^ 1, (j + 1) * KVBLK);
;     SBAR(); qkt(p0, p1, K_lds + b * SK, qr, r32, hi);
;     partialSM(p0, p1, m_reg, mn, al);
;     if (__any(al < 1.f)) { if (hi == 0) al_l[r32] = al; asm volatile("s_waitcnt lgkmcnt(0)" ::: "memory");
; #pragma unroll
;       for (int d = 0; d < 8; ++d)
; #pragma unroll
;         for (int r = 0; r < 16; ++r) o[d][r] *= al_l[crow(r, hi)]; }
;     finishSM(p0, p1, al, l_reg, pa0, pa1, pa2, pa3); SBAR();
;     const int vb = vb0 + b * SV;
;     pv_all(o, vb, pa0, pa1, pa2, pa3);
;     asm volatile("s_waitcnt vmcnt(0) lgkmcnt(0)" ::: "memory"); __builtin_amdgcn_s_barrier(); asm volatile("" ::: "memory");
	v_mfma_f32_32x32x16_bf16 v[98:113], v[130:133], v[156:159], v[98:113]
	ds_read_b64_tr_b16 v[206:207], v251 offset:2048
	ds_read_b64_tr_b16 v[208:209], v251 offset:6144
	ds_read_b64_tr_b16 v[244:245], v251 offset:10240
	ds_read_b64_tr_b16 v[246:247], v251 offset:14336
	v_mfma_f32_32x32x16_bf16 v[98:113], v[134:137], v[194:197], v[98:113]
	s_waitcnt lgkmcnt(8)
	v_mfma_f32_32x32x16_bf16 v[82:97], v[130:133], v[198:201], v[82:97]
	ds_read_b64_tr_b16 v[156:157], v251 offset:2560
	ds_read_b64_tr_b16 v[158:159], v251 offset:6656
	ds_read_b64_tr_b16 v[194:195], v251 offset:10752
	ds_read_b64_tr_b16 v[196:197], v251 offset:14848
	v_mfma_f32_32x32x16_bf16 v[82:97], v[134:137], v[202:205], v[82:97]
	s_waitcnt lgkmcnt(8)
	v_mfma_f32_32x32x16_bf16 v[66:81], v[130:133], v[148:151], v[66:81]
	ds_read_b64_tr_b16 v[198:199], v251 offset:3072
	ds_read_b64_tr_b16 v[200:201], v251 offset:7168
	ds_read_b64_tr_b16 v[202:203], v251 offset:11264
	ds_read_b64_tr_b16 v[204:205], v251 offset:15360
	v_mfma_f32_32x32x16_bf16 v[66:81], v[134:137], v[152:155], v[66:81]
	s_waitcnt lgkmcnt(8)
	v_mfma_f32_32x32x16_bf16 v[50:65], v[130:133], v[206:209], v[50:65]
	ds_read_b64_tr_b16 v[148:149], v251 offset:3584
	ds_read_b64_tr_b16 v[150:151], v251 offset:7680
	ds_read_b64_tr_b16 v[152:153], v251 offset:11776
	ds_read_b64_tr_b16 v[154:155], v251 offset:15872
	v_mfma_f32_32x32x16_bf16 v[50:65], v[134:137], v[244:247], v[50:65]
	s_waitcnt lgkmcnt(8)
	v_mfma_f32_32x32x16_bf16 v[34:49], v[130:133], v[156:159], v[34:49]
	ds_read_b64_tr_b16 v[206:207], v251 offset:16384
	ds_read_b64_tr_b16 v[208:209], v251 offset:20480
	ds_read_b64_tr_b16 v[244:245], v251 offset:24576
	ds_read_b64_tr_b16 v[246:247], v251 offset:28672
	v_mfma_f32_32x32x16_bf16 v[34:49], v[134:137], v[194:197], v[34:49]
	s_waitcnt lgkmcnt(8)
	v_mfma_f32_32x32x16_bf16 v[18:33], v[130:133], v[198:201], v[18:33]
	ds_read_b64_tr_b16 v[156:157], v251 offset:16896
	ds_read_b64_tr_b16 v[158:159], v251 offset:20992
	ds_read_b64_tr_b16 v[194:195], v251 offset:25088
	ds_read_b64_tr_b16 v[196:197], v251 offset:29184
	v_mfma_f32_32x32x16_bf16 v[18:33], v[134:137], v[202:205], v[18:33]
	s_waitcnt lgkmcnt(8)
	v_mfma_f32_32x32x16_bf16 v[2:17], v[130:133], v[148:151], v[2:17]
	ds_read_b64_tr_b16 v[198:199], v251 offset:17408
	ds_read_b64_tr_b16 v[200:201], v251 offset:21504
	ds_read_b64_tr_b16 v[202:203], v251 offset:25600
	ds_read_b64_tr_b16 v[204:205], v251 offset:29696
	v_mfma_f32_32x32x16_bf16 v[2:17], v[134:137], v[152:155], v[2:17]
	s_waitcnt lgkmcnt(8)
	v_mfma_f32_32x32x16_bf16 v[114:129], v[138:141], v[206:209], v[114:129]
	ds_read_b64_tr_b16 v[148:149], v251 offset:17920
	ds_read_b64_tr_b16 v[150:151], v251 offset:22016
	ds_read_b64_tr_b16 v[152:153], v251 offset:26112
	ds_read_b64_tr_b16 v[154:155], v251 offset:30208
	v_mfma_f32_32x32x16_bf16 v[114:129], v[142:145], v[244:247], v[114:129]
	s_waitcnt lgkmcnt(8)
	v_mfma_f32_32x32x16_bf16 v[98:113], v[138:141], v[156:159], v[98:113]
	ds_read_b64_tr_b16 v[206:207], v251 offset:18432
	ds_read_b64_tr_b16 v[208:209], v251 offset:22528
	ds_read_b64_tr_b16 v[244:245], v251 offset:26624
	ds_read_b64_tr_b16 v[246:247], v251 offset:30720
	v_mfma_f32_32x32x16_bf16 v[98:113], v[142:145], v[194:197], v[98:113]
	s_waitcnt lgkmcnt(8)
	v_mfma_f32_32x32x16_bf16 v[82:97], v[138:141], v[198:201], v[82:97]
	ds_read_b64_tr_b16 v[156:157], v251 offset:18944
	ds_read_b64_tr_b16 v[158:159], v251 offset:23040
	ds_read_b64_tr_b16 v[194:195], v251 offset:27136
	ds_read_b64_tr_b16 v[196:197], v251 offset:31232
	v_mfma_f32_32x32x16_bf16 v[82:97], v[142:145], v[202:205], v[82:97]
	s_waitcnt lgkmcnt(8)
	v_mfma_f32_32x32x16_bf16 v[66:81], v[138:141], v[148:151], v[66:81]
	ds_read_b64_tr_b16 v[198:199], v251 offset:19456
	ds_read_b64_tr_b16 v[200:201], v251 offset:23552
	ds_read_b64_tr_b16 v[202:203], v251 offset:27648
	ds_read_b64_tr_b16 v[204:205], v251 offset:31744
	v_mfma_f32_32x32x16_bf16 v[66:81], v[142:145], v[152:155], v[66:81]
	s_waitcnt lgkmcnt(8)
	v_mfma_f32_32x32x16_bf16 v[50:65], v[138:141], v[206:209], v[50:65]
	ds_read_b64_tr_b16 v[148:149], v251 offset:19968
	ds_read_b64_tr_b16 v[150:151], v251 offset:24064
	ds_read_b64_tr_b16 v[152:153], v251 offset:28160
	ds_read_b64_tr_b16 v[154:155], v251 offset:32256
	v_mfma_f32_32x32x16_bf16 v[50:65], v[142:145], v[244:247], v[50:65]
	s_waitcnt lgkmcnt(8)
	v_mfma_f32_32x32x16_bf16 v[34:49], v[138:141], v[156:159], v[34:49]
	v_mfma_f32_32x32x16_bf16 v[34:49], v[142:145], v[194:197], v[34:49]
	s_waitcnt lgkmcnt(4)
	v_mfma_f32_32x32x16_bf16 v[18:33], v[138:141], v[198:201], v[18:33]
	v_mfma_f32_32x32x16_bf16 v[18:33], v[142:145], v[202:205], v[18:33]
	s_waitcnt vmcnt(0) lgkmcnt(0)
	s_barrier
	s_and_b32 s8, s29, 1
	s_lshl_b32 s8, s8, 14
	s_add_i32 s8, s8, 0x10010
	v_add3_u32 v1, s8, v233, v213
	ds_read_b128 v[194:197], v1
	ds_read_b128 v[198:201], v1 offset:8192
	v_add3_u32 v1, s8, v234, v213
	ds_read_b128 v[202:205], v1
	ds_read_b128 v[206:209], v1 offset:8192
	v_add3_u32 v1, s8, v235, v213
	ds_read_b128 v[246:249], v1
	ds_read_b128 v[252:255], v1 offset:8192
	s_cmp_eq_u32 s24, s29
	v_mfma_f32_32x32x16_bf16 v[2:17], v[138:141], v[148:151], v[2:17]
	v_mfma_f32_32x32x16_bf16 v[2:17], v[142:145], v[152:155], v[2:17]
	v_mov_b32_e32 v244, v146
	s_cbranch_scc0 .LBB0_616
	s_branch .LBB0_626
